# SWIGLU epilogue rewritten with packed f32 ops (rstd folded into constants), 9 VALU per 2 outputs
# speedup vs baseline: 1.0110x; 1.0110x over previous
; __device__ __forceinline__ float sigmoidf_(float x) { return __builtin_amdgcn_rcpf(1.f + __expf(-x)); }
; __device__ __forceinline__ float rstd_of(float ssv) { return rsqrtf(ssv * (1.f / 1024.f) + EPS); }
; template <int EPI>
; __device__ __forceinline__ void gemm_epilogue(const f32x4 (&acc)[2][2][4][2], const Unit& u, int wr, int wc, int fr, int fq,
;                                               const EpiArgs& ea, const float (&rs_pre)[2][4]) {
;     ...
;     for (int ai = 0; ai < 2; ++ai)
; #pragma unroll
;       for (int m = 0; m < 4; ++m)
;         rsr[ai][m] = (EPI == EPI_SWIGLU || EPI == EPI_PLEGATE) ? rs_pre[ai][m] : ea.ss_in[row0 + ai * 128 + m * 16];
; #pragma unroll
;     for (int ai = 0; ai < 2; ++ai)
; #pragma unroll
;       for (int m = 0; m < 4; ++m) rsr[ai][m] = rstd_of(rsr[ai][m]);
;   }
;   if constexpr (EPI == EPI_SWIGLU) {
; #pragma unroll
;     for (int ai = 0; ai < 2; ++ai)
; #pragma unroll
;       for (int m = 0; m < 4; ++m) {
;         const int row = row0 + ai * 128 + m * 16;
;         const float rs = rsr[ai][m];
;         u16* rowp = ea.out_bf + (size_t)row * 2816 + u.pn * 128 + wc * 32 + 8 * fq;
;         uint2 hp2[2];
; #pragma unroll
;         for (int n = 0; n < 2; ++n) {
;           f32x4 g = acc[ai][0][m][n] * rs, uu = acc[ai][1][m][n] * rs, h;
; #pragma unroll
;           for (int i = 0; i < 4; ++i) h[i] = g[i] * sigmoidf_(g[i]) * uu[i];
;           hp2[n] = pack4(h);
;         }
;         *reinterpret_cast<uint4*>(rowp) = make_uint4(hp2[0].x, hp2[0].y, hp2[1].x, hp2[1].y);
;       }
.LBB0_918:
	v_fmamk_f32 v162, v149, 0x3a800000, v218
	v_fmamk_f32 v163, v148, 0x3a800000, v218
	v_fmamk_f32 v164, v147, 0x3a800000, v218
	v_fmamk_f32 v165, v146, 0x3a800000, v218
	v_fmamk_f32 v166, v143, 0x3a800000, v218
	v_fmamk_f32 v167, v142, 0x3a800000, v218
	v_fmamk_f32 v168, v141, 0x3a800000, v218
	v_fmamk_f32 v169, v140, 0x3a800000, v218
	v_rsq_f32_e32 v162, v162
	v_rsq_f32_e32 v163, v163
	v_rsq_f32_e32 v164, v164
	v_rsq_f32_e32 v165, v165
	v_rsq_f32_e32 v166, v166
	v_rsq_f32_e32 v167, v167
	v_rsq_f32_e32 v168, v168
	v_rsq_f32_e32 v169, v169
	v_lshl_add_u32 v148, s64, 8, v113
	s_lshl_b32 s36, s72, 7
	s_ashr_i32 s37, s36, 31
	s_lshl_b64 s[60:61], s[36:37], 1
	v_readlane_b32 s12, v254, 16
	s_lshl_b32 s94, s12, 1
	v_mul_lo_u32 v160, v148, s3
	v_add_u32_e32 v160, s60, v160
	v_add_u32_e32 v160, s94, v160
	v_add_u32_e32 v160, v160, v138
	v_mul_f32_e32 v170, 0xbfb8aa3b, v162
	v_mul_f32_e32 v172, v162, v162
	v_pk_mul_f32 v[174:175], v[126:127], v[170:171] op_sel_hi:[1,0]
	v_pk_mul_f32 v[176:177], v[128:129], v[170:171] op_sel_hi:[1,0]
	v_exp_f32_e32 v174, v174
	v_exp_f32_e32 v176, v176
	v_exp_f32_e32 v175, v175
	v_exp_f32_e32 v177, v177
	v_pk_mul_f32 v[122:123], v[126:127], v[122:123]
	v_pk_mul_f32 v[124:125], v[128:129], v[124:125]
	v_pk_add_f32 v[174:175], v[174:175], 1.0 op_sel_hi:[1,0]
	v_pk_add_f32 v[176:177], v[176:177], 1.0 op_sel_hi:[1,0]
	v_rcp_f32_e32 v174, v174
	v_rcp_f32_e32 v176, v176
	v_rcp_f32_e32 v175, v175
	v_rcp_f32_e32 v177, v177
	v_pk_mul_f32 v[174:175], v[174:175], v[172:173] op_sel_hi:[1,0]
	v_pk_mul_f32 v[176:177], v[176:177], v[172:173] op_sel_hi:[1,0]
	v_pk_mul_f32 v[126:127], v[122:123], v[174:175]
	v_pk_mul_f32 v[128:129], v[124:125], v[176:177]
	v_pk_mul_f32 v[174:175], v[118:119], v[170:171] op_sel_hi:[1,0]
	v_pk_mul_f32 v[176:177], v[120:121], v[170:171] op_sel_hi:[1,0]
	v_exp_f32_e32 v174, v174
	v_exp_f32_e32 v176, v176
	v_exp_f32_e32 v175, v175
	v_exp_f32_e32 v177, v177
	v_pk_mul_f32 v[114:115], v[118:119], v[114:115]
	v_pk_mul_f32 v[116:117], v[120:121], v[116:117]
	v_pk_add_f32 v[174:175], v[174:175], 1.0 op_sel_hi:[1,0]
	v_pk_add_f32 v[176:177], v[176:177], 1.0 op_sel_hi:[1,0]
	v_rcp_f32_e32 v174, v174
	v_rcp_f32_e32 v176, v176
	v_rcp_f32_e32 v175, v175
	v_rcp_f32_e32 v177, v177
	v_pk_mul_f32 v[174:175], v[174:175], v[172:173] op_sel_hi:[1,0]
	v_pk_mul_f32 v[176:177], v[176:177], v[172:173] op_sel_hi:[1,0]
	v_pk_mul_f32 v[118:119], v[114:115], v[174:175]
	v_pk_mul_f32 v[120:121], v[116:117], v[176:177]
	v_cvt_pk_bf16_f32 v126, v126, v127
	v_cvt_pk_bf16_f32 v127, v128, v129
	v_cvt_pk_bf16_f32 v128, v118, v119
	v_cvt_pk_bf16_f32 v129, v120, v121
	global_store_dwordx4 v160, v[126:129], s[42:43]
	v_mul_f32_e32 v170, 0xbfb8aa3b, v163
	v_mul_f32_e32 v172, v163, v163
	v_pk_mul_f32 v[174:175], v[108:109], v[170:171] op_sel_hi:[1,0]
	v_pk_mul_f32 v[176:177], v[110:111], v[170:171] op_sel_hi:[1,0]
	v_exp_f32_e32 v174, v174
	v_exp_f32_e32 v176, v176
	v_exp_f32_e32 v175, v175
	v_exp_f32_e32 v177, v177
	v_pk_mul_f32 v[104:105], v[108:109], v[104:105]
	v_pk_mul_f32 v[106:107], v[110:111], v[106:107]
	v_pk_add_f32 v[174:175], v[174:175], 1.0 op_sel_hi:[1,0]
	v_pk_add_f32 v[176:177], v[176:177], 1.0 op_sel_hi:[1,0]
	v_rcp_f32_e32 v174, v174
	v_rcp_f32_e32 v176, v176
	v_rcp_f32_e32 v175, v175
	v_rcp_f32_e32 v177, v177
	v_pk_mul_f32 v[174:175], v[174:175], v[172:173] op_sel_hi:[1,0]
	v_pk_mul_f32 v[176:177], v[176:177], v[172:173] op_sel_hi:[1,0]
	v_pk_mul_f32 v[108:109], v[104:105], v[174:175]
	v_pk_mul_f32 v[110:111], v[106:107], v[176:177]
	v_pk_mul_f32 v[174:175], v[100:101], v[170:171] op_sel_hi:[1,0]
	v_pk_mul_f32 v[176:177], v[102:103], v[170:171] op_sel_hi:[1,0]
	v_exp_f32_e32 v174, v174
	v_exp_f32_e32 v176, v176
	v_exp_f32_e32 v175, v175
	v_exp_f32_e32 v177, v177
	v_pk_mul_f32 v[96:97], v[100:101], v[96:97]
	v_pk_mul_f32 v[98:99], v[102:103], v[98:99]
	v_pk_add_f32 v[174:175], v[174:175], 1.0 op_sel_hi:[1,0]
	v_pk_add_f32 v[176:177], v[176:177], 1.0 op_sel_hi:[1,0]
	v_rcp_f32_e32 v174, v174
	v_rcp_f32_e32 v176, v176
	v_rcp_f32_e32 v175, v175
	v_rcp_f32_e32 v177, v177
	v_pk_mul_f32 v[174:175], v[174:175], v[172:173] op_sel_hi:[1,0]
	v_pk_mul_f32 v[176:177], v[176:177], v[172:173] op_sel_hi:[1,0]
	v_pk_mul_f32 v[100:101], v[96:97], v[174:175]
	v_pk_mul_f32 v[102:103], v[98:99], v[176:177]
	v_cvt_pk_bf16_f32 v108, v108, v109
	v_cvt_pk_bf16_f32 v109, v110, v111
	v_cvt_pk_bf16_f32 v110, v100, v101
	v_cvt_pk_bf16_f32 v111, v102, v103
	s_mul_i32 s37, s3, 16
	v_add_u32_e32 v161, s37, v160
	global_store_dwordx4 v161, v[108:111], s[42:43]
	v_mul_f32_e32 v170, 0xbfb8aa3b, v164
	v_mul_f32_e32 v172, v164, v164
	v_pk_mul_f32 v[174:175], v[92:93], v[170:171] op_sel_hi:[1,0]
	v_pk_mul_f32 v[176:177], v[94:95], v[170:171] op_sel_hi:[1,0]
	v_exp_f32_e32 v174, v174
	v_exp_f32_e32 v176, v176
	v_exp_f32_e32 v175, v175
	v_exp_f32_e32 v177, v177
	v_pk_mul_f32 v[88:89], v[92:93], v[88:89]
	v_pk_mul_f32 v[90:91], v[94:95], v[90:91]
	v_pk_add_f32 v[174:175], v[174:175], 1.0 op_sel_hi:[1,0]
	v_pk_add_f32 v[176:177], v[176:177], 1.0 op_sel_hi:[1,0]
	v_rcp_f32_e32 v174, v174
	v_rcp_f32_e32 v176, v176
	v_rcp_f32_e32 v175, v175
	v_rcp_f32_e32 v177, v177
	v_pk_mul_f32 v[174:175], v[174:175], v[172:173] op_sel_hi:[1,0]
	v_pk_mul_f32 v[176:177], v[176:177], v[172:173] op_sel_hi:[1,0]
	v_pk_mul_f32 v[92:93], v[88:89], v[174:175]
	v_pk_mul_f32 v[94:95], v[90:91], v[176:177]
	v_pk_mul_f32 v[174:175], v[84:85], v[170:171] op_sel_hi:[1,0]
	v_pk_mul_f32 v[176:177], v[86:87], v[170:171] op_sel_hi:[1,0]
	v_exp_f32_e32 v174, v174
	v_exp_f32_e32 v176, v176
	v_exp_f32_e32 v175, v175
	v_exp_f32_e32 v177, v177
	v_pk_mul_f32 v[80:81], v[84:85], v[80:81]
; __device__ __forceinline__ float sigmoidf_(float x) { return __builtin_amdgcn_rcpf(1.f + __expf(-x)); }
; template <int EPI>
; __device__ __forceinline__ void gemm_epilogue(const f32x4 (&acc)[2][2][4][2], const Unit& u, int wr, int wc, int fr, int fq,
;                                               const EpiArgs& ea, const float (&rs_pre)[2][4]) {
;     ...
;   if constexpr (EPI == EPI_SWIGLU) {
; #pragma unroll
;     for (int ai = 0; ai < 2; ++ai)
; #pragma unroll
;       for (int m = 0; m < 4; ++m) {
;         const int row = row0 + ai * 128 + m * 16;
;         const float rs = rsr[ai][m];
;         u16* rowp = ea.out_bf + (size_t)row * 2816 + u.pn * 128 + wc * 32 + 8 * fq;
;         uint2 hp2[2];
; #pragma unroll
;         for (int n = 0; n < 2; ++n) {
;           f32x4 g = acc[ai][0][m][n] * rs, uu = acc[ai][1][m][n] * rs, h;
; #pragma unroll
;           for (int i = 0; i < 4; ++i) h[i] = g[i] * sigmoidf_(g[i]) * uu[i];
;           hp2[n] = pack4(h);
;         }
;         *reinterpret_cast<uint4*>(rowp) = make_uint4(hp2[0].x, hp2[0].y, hp2[1].x, hp2[1].y);
;       }
	v_pk_mul_f32 v[82:83], v[86:87], v[82:83]
	v_pk_add_f32 v[174:175], v[174:175], 1.0 op_sel_hi:[1,0]
	v_pk_add_f32 v[176:177], v[176:177], 1.0 op_sel_hi:[1,0]
	v_rcp_f32_e32 v174, v174
	v_rcp_f32_e32 v176, v176
	v_rcp_f32_e32 v175, v175
	v_rcp_f32_e32 v177, v177
	v_pk_mul_f32 v[174:175], v[174:175], v[172:173] op_sel_hi:[1,0]
	v_pk_mul_f32 v[176:177], v[176:177], v[172:173] op_sel_hi:[1,0]
	v_pk_mul_f32 v[84:85], v[80:81], v[174:175]
	v_pk_mul_f32 v[86:87], v[82:83], v[176:177]
	v_cvt_pk_bf16_f32 v92, v92, v93
	v_cvt_pk_bf16_f32 v93, v94, v95
	v_cvt_pk_bf16_f32 v94, v84, v85
	v_cvt_pk_bf16_f32 v95, v86, v87
	s_mul_i32 s37, s3, 32
	v_add_u32_e32 v161, s37, v160
	global_store_dwordx4 v161, v[92:95], s[42:43]
	v_mul_f32_e32 v170, 0xbfb8aa3b, v165
	v_mul_f32_e32 v172, v165, v165
	v_pk_mul_f32 v[174:175], v[76:77], v[170:171] op_sel_hi:[1,0]
	v_pk_mul_f32 v[176:177], v[78:79], v[170:171] op_sel_hi:[1,0]
	v_exp_f32_e32 v174, v174
	v_exp_f32_e32 v176, v176
	v_exp_f32_e32 v175, v175
	v_exp_f32_e32 v177, v177
	v_pk_mul_f32 v[72:73], v[76:77], v[72:73]
	v_pk_mul_f32 v[74:75], v[78:79], v[74:75]
	v_pk_add_f32 v[174:175], v[174:175], 1.0 op_sel_hi:[1,0]
	v_pk_add_f32 v[176:177], v[176:177], 1.0 op_sel_hi:[1,0]
	v_rcp_f32_e32 v174, v174
	v_rcp_f32_e32 v176, v176
	v_rcp_f32_e32 v175, v175
	v_rcp_f32_e32 v177, v177
	v_pk_mul_f32 v[174:175], v[174:175], v[172:173] op_sel_hi:[1,0]
	v_pk_mul_f32 v[176:177], v[176:177], v[172:173] op_sel_hi:[1,0]
	v_pk_mul_f32 v[76:77], v[72:73], v[174:175]
	v_pk_mul_f32 v[78:79], v[74:75], v[176:177]
	v_pk_mul_f32 v[174:175], v[68:69], v[170:171] op_sel_hi:[1,0]
	v_pk_mul_f32 v[176:177], v[70:71], v[170:171] op_sel_hi:[1,0]
	v_exp_f32_e32 v174, v174
	v_exp_f32_e32 v176, v176
	v_exp_f32_e32 v175, v175
	v_exp_f32_e32 v177, v177
	v_pk_mul_f32 v[64:65], v[68:69], v[64:65]
	v_pk_mul_f32 v[66:67], v[70:71], v[66:67]
	v_pk_add_f32 v[174:175], v[174:175], 1.0 op_sel_hi:[1,0]
	v_pk_add_f32 v[176:177], v[176:177], 1.0 op_sel_hi:[1,0]
	v_rcp_f32_e32 v174, v174
	v_rcp_f32_e32 v176, v176
	v_rcp_f32_e32 v175, v175
	v_rcp_f32_e32 v177, v177
	v_pk_mul_f32 v[174:175], v[174:175], v[172:173] op_sel_hi:[1,0]
	v_pk_mul_f32 v[176:177], v[176:177], v[172:173] op_sel_hi:[1,0]
	v_pk_mul_f32 v[68:69], v[64:65], v[174:175]
	v_pk_mul_f32 v[70:71], v[66:67], v[176:177]
	v_cvt_pk_bf16_f32 v76, v76, v77
	v_cvt_pk_bf16_f32 v77, v78, v79
	v_cvt_pk_bf16_f32 v78, v68, v69
	v_cvt_pk_bf16_f32 v79, v70, v71
	s_mul_i32 s37, s3, 48
	v_add_u32_e32 v161, s37, v160
	global_store_dwordx4 v161, v[76:79], s[42:43]
	v_mul_f32_e32 v170, 0xbfb8aa3b, v166
	v_mul_f32_e32 v172, v166, v166
	v_pk_mul_f32 v[174:175], v[60:61], v[170:171] op_sel_hi:[1,0]
	v_pk_mul_f32 v[176:177], v[62:63], v[170:171] op_sel_hi:[1,0]
	v_exp_f32_e32 v174, v174
	v_exp_f32_e32 v176, v176
	v_exp_f32_e32 v175, v175
	v_exp_f32_e32 v177, v177
	v_pk_mul_f32 v[56:57], v[60:61], v[56:57]
	v_pk_mul_f32 v[58:59], v[62:63], v[58:59]
	v_pk_add_f32 v[174:175], v[174:175], 1.0 op_sel_hi:[1,0]
	v_pk_add_f32 v[176:177], v[176:177], 1.0 op_sel_hi:[1,0]
	v_rcp_f32_e32 v174, v174
	v_rcp_f32_e32 v176, v176
	v_rcp_f32_e32 v175, v175
	v_rcp_f32_e32 v177, v177
	v_pk_mul_f32 v[174:175], v[174:175], v[172:173] op_sel_hi:[1,0]
	v_pk_mul_f32 v[176:177], v[176:177], v[172:173] op_sel_hi:[1,0]
	v_pk_mul_f32 v[60:61], v[56:57], v[174:175]
	v_pk_mul_f32 v[62:63], v[58:59], v[176:177]
	v_pk_mul_f32 v[174:175], v[52:53], v[170:171] op_sel_hi:[1,0]
	v_pk_mul_f32 v[176:177], v[54:55], v[170:171] op_sel_hi:[1,0]
	v_exp_f32_e32 v174, v174
	v_exp_f32_e32 v176, v176
	v_exp_f32_e32 v175, v175
	v_exp_f32_e32 v177, v177
	v_pk_mul_f32 v[48:49], v[52:53], v[48:49]
	v_pk_mul_f32 v[50:51], v[54:55], v[50:51]
	v_pk_add_f32 v[174:175], v[174:175], 1.0 op_sel_hi:[1,0]
	v_pk_add_f32 v[176:177], v[176:177], 1.0 op_sel_hi:[1,0]
	v_rcp_f32_e32 v174, v174
	v_rcp_f32_e32 v176, v176
	v_rcp_f32_e32 v175, v175
	v_rcp_f32_e32 v177, v177
	v_pk_mul_f32 v[174:175], v[174:175], v[172:173] op_sel_hi:[1,0]
	v_pk_mul_f32 v[176:177], v[176:177], v[172:173] op_sel_hi:[1,0]
	v_pk_mul_f32 v[52:53], v[48:49], v[174:175]
	v_pk_mul_f32 v[54:55], v[50:51], v[176:177]
	v_cvt_pk_bf16_f32 v60, v60, v61
	v_cvt_pk_bf16_f32 v61, v62, v63
	v_cvt_pk_bf16_f32 v62, v52, v53
	v_cvt_pk_bf16_f32 v63, v54, v55
	s_mul_i32 s37, s3, 128
	v_add_u32_e32 v161, s37, v160
	global_store_dwordx4 v161, v[60:63], s[42:43]
	v_mul_f32_e32 v170, 0xbfb8aa3b, v167
	v_mul_f32_e32 v172, v167, v167
	v_pk_mul_f32 v[174:175], v[44:45], v[170:171] op_sel_hi:[1,0]
	v_pk_mul_f32 v[176:177], v[46:47], v[170:171] op_sel_hi:[1,0]
	v_exp_f32_e32 v174, v174
	v_exp_f32_e32 v176, v176
	v_exp_f32_e32 v175, v175
	v_exp_f32_e32 v177, v177
	v_pk_mul_f32 v[40:41], v[44:45], v[40:41]
	v_pk_mul_f32 v[42:43], v[46:47], v[42:43]
	v_pk_add_f32 v[174:175], v[174:175], 1.0 op_sel_hi:[1,0]
	v_pk_add_f32 v[176:177], v[176:177], 1.0 op_sel_hi:[1,0]
	v_rcp_f32_e32 v174, v174
	v_rcp_f32_e32 v176, v176
	v_rcp_f32_e32 v175, v175
	v_rcp_f32_e32 v177, v177
	v_pk_mul_f32 v[174:175], v[174:175], v[172:173] op_sel_hi:[1,0]
	v_pk_mul_f32 v[176:177], v[176:177], v[172:173] op_sel_hi:[1,0]
	v_pk_mul_f32 v[44:45], v[40:41], v[174:175]
	v_pk_mul_f32 v[46:47], v[42:43], v[176:177]
; __device__ __forceinline__ float sigmoidf_(float x) { return __builtin_amdgcn_rcpf(1.f + __expf(-x)); }
; template <int EPI>
; __device__ __forceinline__ void gemm_epilogue(const f32x4 (&acc)[2][2][4][2], const Unit& u, int wr, int wc, int fr, int fq,
;                                               const EpiArgs& ea, const float (&rs_pre)[2][4]) {
;     ...
;   if constexpr (EPI == EPI_SWIGLU) {
; #pragma unroll
;     for (int ai = 0; ai < 2; ++ai)
; #pragma unroll
;       for (int m = 0; m < 4; ++m) {
;         const int row = row0 + ai * 128 + m * 16;
;         const float rs = rsr[ai][m];
;         u16* rowp = ea.out_bf + (size_t)row * 2816 + u.pn * 128 + wc * 32 + 8 * fq;
;         uint2 hp2[2];
; #pragma unroll
;         for (int n = 0; n < 2; ++n) {
;           f32x4 g = acc[ai][0][m][n] * rs, uu = acc[ai][1][m][n] * rs, h;
; #pragma unroll
;           for (int i = 0; i < 4; ++i) h[i] = g[i] * sigmoidf_(g[i]) * uu[i];
;           hp2[n] = pack4(h);
;         }
;         *reinterpret_cast<uint4*>(rowp) = make_uint4(hp2[0].x, hp2[0].y, hp2[1].x, hp2[1].y);
;       }
	v_pk_mul_f32 v[174:175], v[36:37], v[170:171] op_sel_hi:[1,0]
	v_pk_mul_f32 v[176:177], v[38:39], v[170:171] op_sel_hi:[1,0]
	v_exp_f32_e32 v174, v174
	v_exp_f32_e32 v176, v176
	v_exp_f32_e32 v175, v175
	v_exp_f32_e32 v177, v177
	v_pk_mul_f32 v[32:33], v[36:37], v[32:33]
	v_pk_mul_f32 v[34:35], v[38:39], v[34:35]
	v_pk_add_f32 v[174:175], v[174:175], 1.0 op_sel_hi:[1,0]
	v_pk_add_f32 v[176:177], v[176:177], 1.0 op_sel_hi:[1,0]
	v_rcp_f32_e32 v174, v174
	v_rcp_f32_e32 v176, v176
	v_rcp_f32_e32 v175, v175
	v_rcp_f32_e32 v177, v177
	v_pk_mul_f32 v[174:175], v[174:175], v[172:173] op_sel_hi:[1,0]
	v_pk_mul_f32 v[176:177], v[176:177], v[172:173] op_sel_hi:[1,0]
	v_pk_mul_f32 v[36:37], v[32:33], v[174:175]
	v_pk_mul_f32 v[38:39], v[34:35], v[176:177]
	v_cvt_pk_bf16_f32 v44, v44, v45
	v_cvt_pk_bf16_f32 v45, v46, v47
	v_cvt_pk_bf16_f32 v46, v36, v37
	v_cvt_pk_bf16_f32 v47, v38, v39
	s_mul_i32 s37, s3, 144
	v_add_u32_e32 v161, s37, v160
	global_store_dwordx4 v161, v[44:47], s[42:43]
	v_mul_f32_e32 v170, 0xbfb8aa3b, v168
	v_mul_f32_e32 v172, v168, v168
	v_pk_mul_f32 v[174:175], v[28:29], v[170:171] op_sel_hi:[1,0]
	v_pk_mul_f32 v[176:177], v[30:31], v[170:171] op_sel_hi:[1,0]
	v_exp_f32_e32 v174, v174
	v_exp_f32_e32 v176, v176
	v_exp_f32_e32 v175, v175
	v_exp_f32_e32 v177, v177
	v_pk_mul_f32 v[24:25], v[28:29], v[24:25]
	v_pk_mul_f32 v[26:27], v[30:31], v[26:27]
	v_pk_add_f32 v[174:175], v[174:175], 1.0 op_sel_hi:[1,0]
	v_pk_add_f32 v[176:177], v[176:177], 1.0 op_sel_hi:[1,0]
	v_rcp_f32_e32 v174, v174
	v_rcp_f32_e32 v176, v176
	v_rcp_f32_e32 v175, v175
	v_rcp_f32_e32 v177, v177
	v_pk_mul_f32 v[174:175], v[174:175], v[172:173] op_sel_hi:[1,0]
	v_pk_mul_f32 v[176:177], v[176:177], v[172:173] op_sel_hi:[1,0]
	v_pk_mul_f32 v[28:29], v[24:25], v[174:175]
	v_pk_mul_f32 v[30:31], v[26:27], v[176:177]
	v_pk_mul_f32 v[174:175], v[20:21], v[170:171] op_sel_hi:[1,0]
	v_pk_mul_f32 v[176:177], v[22:23], v[170:171] op_sel_hi:[1,0]
	v_exp_f32_e32 v174, v174
	v_exp_f32_e32 v176, v176
	v_exp_f32_e32 v175, v175
	v_exp_f32_e32 v177, v177
	v_pk_mul_f32 v[16:17], v[20:21], v[16:17]
	v_pk_mul_f32 v[18:19], v[22:23], v[18:19]
	v_pk_add_f32 v[174:175], v[174:175], 1.0 op_sel_hi:[1,0]
	v_pk_add_f32 v[176:177], v[176:177], 1.0 op_sel_hi:[1,0]
	v_rcp_f32_e32 v174, v174
	v_rcp_f32_e32 v176, v176
	v_rcp_f32_e32 v175, v175
	v_rcp_f32_e32 v177, v177
	v_pk_mul_f32 v[174:175], v[174:175], v[172:173] op_sel_hi:[1,0]
	v_pk_mul_f32 v[176:177], v[176:177], v[172:173] op_sel_hi:[1,0]
	v_pk_mul_f32 v[20:21], v[16:17], v[174:175]
	v_pk_mul_f32 v[22:23], v[18:19], v[176:177]
	v_cvt_pk_bf16_f32 v28, v28, v29
	v_cvt_pk_bf16_f32 v29, v30, v31
	v_cvt_pk_bf16_f32 v30, v20, v21
	v_cvt_pk_bf16_f32 v31, v22, v23
	s_mul_i32 s37, s3, 160
	v_add_u32_e32 v161, s37, v160
	global_store_dwordx4 v161, v[28:31], s[42:43]
	v_mul_f32_e32 v170, 0xbfb8aa3b, v169
	v_mul_f32_e32 v172, v169, v169
	v_pk_mul_f32 v[174:175], v[12:13], v[170:171] op_sel_hi:[1,0]
	v_pk_mul_f32 v[176:177], v[14:15], v[170:171] op_sel_hi:[1,0]
	v_exp_f32_e32 v174, v174
	v_exp_f32_e32 v176, v176
	v_exp_f32_e32 v175, v175
	v_exp_f32_e32 v177, v177
	v_pk_mul_f32 v[8:9], v[12:13], v[8:9]
	v_pk_mul_f32 v[10:11], v[14:15], v[10:11]
	v_pk_add_f32 v[174:175], v[174:175], 1.0 op_sel_hi:[1,0]
	v_pk_add_f32 v[176:177], v[176:177], 1.0 op_sel_hi:[1,0]
	v_rcp_f32_e32 v174, v174
	v_rcp_f32_e32 v176, v176
	v_rcp_f32_e32 v175, v175
	v_rcp_f32_e32 v177, v177
	v_pk_mul_f32 v[174:175], v[174:175], v[172:173] op_sel_hi:[1,0]
	v_pk_mul_f32 v[176:177], v[176:177], v[172:173] op_sel_hi:[1,0]
	v_pk_mul_f32 v[12:13], v[8:9], v[174:175]
	v_pk_mul_f32 v[14:15], v[10:11], v[176:177]
	v_pk_mul_f32 v[174:175], v[4:5], v[170:171] op_sel_hi:[1,0]
	v_pk_mul_f32 v[176:177], v[6:7], v[170:171] op_sel_hi:[1,0]
	v_exp_f32_e32 v174, v174
	v_exp_f32_e32 v176, v176
	v_exp_f32_e32 v175, v175
	v_exp_f32_e32 v177, v177
	v_pk_mul_f32 v[0:1], v[4:5], v[0:1]
	v_pk_mul_f32 v[2:3], v[6:7], v[2:3]
	v_pk_add_f32 v[174:175], v[174:175], 1.0 op_sel_hi:[1,0]
	v_pk_add_f32 v[176:177], v[176:177], 1.0 op_sel_hi:[1,0]
	v_rcp_f32_e32 v174, v174
	v_rcp_f32_e32 v176, v176
	v_rcp_f32_e32 v175, v175
	v_rcp_f32_e32 v177, v177
	v_pk_mul_f32 v[174:175], v[174:175], v[172:173] op_sel_hi:[1,0]
	v_pk_mul_f32 v[176:177], v[176:177], v[172:173] op_sel_hi:[1,0]
	v_pk_mul_f32 v[4:5], v[0:1], v[174:175]
	v_pk_mul_f32 v[6:7], v[2:3], v[176:177]
	v_cvt_pk_bf16_f32 v12, v12, v13
	v_cvt_pk_bf16_f32 v13, v14, v15
	v_cvt_pk_bf16_f32 v14, v4, v5
	v_cvt_pk_bf16_f32 v15, v6, v7
	s_mul_i32 s37, s3, 176
	v_add_u32_e32 v161, s37, v160
	global_store_dwordx4 v161, v[12:15], s[42:43]
	s_and_b64 vcc, exec, s[0:1]
	s_mov_b64 s[36:37], -1
	s_cbranch_vccnz .LBB0_903
	v_lshl_add_u32 v0, s71, 8, v113
	v_ashrrev_i32_e32 v1, 31, v0
	v_lshl_add_u64 v[0:1], v[0:1], 2, s[4:5]
	global_load_dword v149, v[0:1], off
	global_load_dword v148, v[0:1], off offset:64
	global_load_dword v147, v[0:1], off offset:128
	global_load_dword v146, v[0:1], off offset:192
	global_load_dword v143, v[0:1], off offset:512
	global_load_dword v142, v[0:1], off offset:576
	global_load_dword v141, v[0:1], off offset:640
	global_load_dword v140, v[0:1], off offset:704
	s_mov_b64 s[36:37], 0
	s_branch .LBB0_903
